# all eight weight conversions (incl. LayerNorm-gain fold variants) through one hand-written 3-deep pipelined routine; DPP reductions for the fold sums
# speedup vs baseline: 1.0071x; 1.0006x over previous
; template <bool FOLD>
; __device__ __forceinline__ void tconv_mat(const float* W, int K, int N, bf16_t* WT, const float* gam, const float* bet, float* cs, float* bw, LAS float* scr) {
;     const int tkn = K / 64, tnn = N / 64, nt = tkn * tnn, tid = threadIdx.x;
;     const int kk = tid >> 4, n4 = (tid & 15) * 4, n = tid >> 3, k8 = (tid & 7) * 8;
;     int it = blockIdx.x; if (it >= nt) return;
;     f32x4 v0, v1;
;     { const int tk = it / tnn, tn = it % tnn; const float* p = W + (size_t)(tk * 64 + kk) * N + tn * 64 + n4; v0 = __builtin_nontemporal_load((const f32x4*)p); v1 = __builtin_nontemporal_load((const f32x4*)(p + (size_t)32 * N)); }
;     for (;;) {
;         const int tk = it / tnn, tn = it % tnn, nx = it + (int)gridDim.x;
;         const f32x4 w0 = v0, w1 = v1;
;         if (nx < nt) { const int tk2 = nx / tnn, tn2 = nx % tnn; const float* p = W + (size_t)(tk2 * 64 + kk) * N + tn2 * 64 + n4; v0 = __builtin_nontemporal_load((const f32x4*)p); v1 = __builtin_nontemporal_load((const f32x4*)(p + (size_t)32 * N)); }
.LtcA_entry:
	v_lshrrev_b32_e32 v88, 4, v241
	v_and_b32_e32 v89, 15, v241
	v_lshlrev_b32_e32 v89, 2, v89
	v_lshrrev_b32_e32 v90, 3, v241
	v_and_b32_e32 v91, 7, v241
	v_lshlrev_b32_e32 v91, 3, v91
	v_mul_lo_u32 v92, v88, s42
	v_lshl_add_u32 v92, v89, 2, v92
	v_mul_u32_u24_e32 v93, 0x104, v89
	v_lshl_add_u32 v93, v88, 2, v93
	v_mul_u32_u24_e32 v94, 0x104, v90
	v_lshl_add_u32 v94, v91, 2, v94
	v_mul_lo_u32 v95, v90, s43
	v_lshl_add_u32 v95, v91, 1, v95
	s_lshl_b32 s46, s42, 5
	s_lshl_b32 s47, s42, 6
	s_lshl_b32 s48, s43, 6
	s_mov_b32 s49, s2
	s_mov_b32 s50, 0
	s_mov_b32 s51, 0
	s_lshl_b32 s58, s16, 1
	s_mul_i32 s34, s16, 3
	s_cmp_lt_u32 s49, s41
	s_cbranch_scc0 .LtcA_done
	s_mov_b32 s52, s49
	s_mul_hi_u32 s54, s52, s44
	s_mul_i32 s55, s54, s40
	s_sub_u32 s55, s52, s55
	s_mul_i32 s56, s54, s47
	s_lshl_b32 s57, s55, 8
	s_add_u32 s56, s56, s57
	v_add_u32_e32 v74, s56, v92
	v_add_u32_e32 v75, s46, v74
	global_load_dwordx4 v[50:53], v74, s[36:37] nt
	global_load_dwordx4 v[54:57], v75, s[36:37] nt
	s_add_u32 s52, s52, s16
	s_cmp_lt_u32 s52, s41
	s_cbranch_scc0 .LtcA_body0
	s_mul_hi_u32 s54, s52, s44
	s_mul_i32 s55, s54, s40
	s_sub_u32 s55, s52, s55
	s_mul_i32 s56, s54, s47
	s_lshl_b32 s57, s55, 8
	s_add_u32 s56, s56, s57
	v_add_u32_e32 v74, s56, v92
	v_add_u32_e32 v75, s46, v74
	global_load_dwordx4 v[58:61], v74, s[36:37] nt
	global_load_dwordx4 v[62:65], v75, s[36:37] nt
	s_add_u32 s52, s52, s16
	s_cmp_lt_u32 s52, s41
	s_cbranch_scc0 .LtcA_body0
	s_mul_hi_u32 s54, s52, s44
	s_mul_i32 s55, s54, s40
	s_sub_u32 s55, s52, s55
	s_mul_i32 s56, s54, s47
	s_lshl_b32 s57, s55, 8
	s_add_u32 s56, s56, s57
	v_add_u32_e32 v74, s56, v92
	v_add_u32_e32 v75, s46, v74
	global_load_dwordx4 v[66:69], v74, s[36:37] nt
	global_load_dwordx4 v[70:73], v75, s[36:37] nt

; __device__ __forceinline__ unsigned pk2(float lo, float hi) { return pg8::cvt_pk_bf16(lo, hi); }
; template <bool FOLD>
; __device__ __forceinline__ void tconv_mat(const float* W, int K, int N, bf16_t* WT, const float* gam, const float* bet, float* cs, float* bw, LAS float* scr) {
;     ...
;         if (nx < nt) { const int tk2 = nx / tnn, tn2 = nx % tnn; const float* p = W + (size_t)(tk2 * 64 + kk) * N + tn2 * 64 + n4; v0 = __builtin_nontemporal_load((const f32x4*)p); v1 = __builtin_nontemporal_load((const f32x4*)(p + (size_t)32 * N)); }
;         scr[(n4 + 0) * 65 + kk] = w0[0]; scr[(n4 + 1) * 65 + kk] = w0[1]; scr[(n4 + 2) * 65 + kk] = w0[2]; scr[(n4 + 3) * 65 + kk] = w0[3];
;         scr[(n4 + 0) * 65 + kk + 32] = w1[0]; scr[(n4 + 1) * 65 + kk + 32] = w1[1]; scr[(n4 + 2) * 65 + kk + 32] = w1[2]; scr[(n4 + 3) * 65 + kk + 32] = w1[3];
;         __syncthreads();
;         { float x[8]; float bsum = 0.f, csum = 0.f;
;           if (FOLD) { const f32x4 g0 = *(const f32x4*)(gam + tk * 64 + k8), g1 = *(const f32x4*)(gam + tk * 64 + k8 + 4), b0 = *(const f32x4*)(bet + tk * 64 + k8), b1 = *(const f32x4*)(bet + tk * 64 + k8 + 4);
; #pragma unroll
;               for (int j = 0; j < 8; ++j) { const float xv = scr[n * 65 + k8 + j]; bsum += xv * (j < 4 ? b0[j & 3] : b1[j & 3]); x[j] = xv * (j < 4 ? g0[j & 3] : g1[j & 3]); }
;           } else {
; #pragma unroll
;               for (int j = 0; j < 8; ++j) x[j] = scr[n * 65 + k8 + j]; }
;           u32x4 w; w.x = pk2(x[0], x[1]); w.y = pk2(x[2], x[3]); w.z = pk2(x[4], x[5]); w.w = pk2(x[6], x[7]);
;           *(u32x4*)(WT + (size_t)(tn * 64 + n) * K + tk * 64 + k8) = w;
.LtcA_wd_0:
	s_mul_hi_u32 s54, s49, s44
	s_mul_i32 s55, s54, s40
	s_sub_u32 s55, s49, s55
	v_add_u32_e32 v76, s51, v93
	ds_write2_b32 v76, v50, v54 offset1:32
	ds_write2_b32 v76, v51, v55 offset0:65 offset1:97
	ds_write2_b32 v76, v52, v56 offset0:130 offset1:162
	ds_write2_b32 v76, v53, v57 offset0:195 offset1:227
	s_waitcnt lgkmcnt(0)
	s_barrier
	s_mul_i32 s56, s55, s48
	s_lshl_b32 s57, s54, 7
	s_add_u32 s56, s56, s57
	v_add_u32_e32 v78, s56, v95
	s_add_u32 s52, s49, s34
	s_cmp_lt_u32 s52, s41
	s_cbranch_scc0 .LtcA_nl_0
	s_mul_hi_u32 s54, s52, s44
	s_mul_i32 s55, s54, s40
	s_sub_u32 s55, s52, s55
	s_mul_i32 s56, s54, s47
	s_lshl_b32 s57, s55, 8
	s_add_u32 s56, s56, s57
	v_add_u32_e32 v74, s56, v92
	v_add_u32_e32 v75, s46, v74
	global_load_dwordx4 v[50:53], v74, s[36:37] nt
	global_load_dwordx4 v[54:57], v75, s[36:37] nt
.LtcA_nl_0:
	v_add_u32_e32 v77, s51, v94
	ds_read2_b32 v[80:81], v77 offset1:1
	ds_read2_b32 v[82:83], v77 offset0:2 offset1:3
	ds_read2_b32 v[84:85], v77 offset0:4 offset1:5
	ds_read2_b32 v[86:87], v77 offset0:6 offset1:7
	s_waitcnt lgkmcnt(0)
	v_cvt_pk_bf16_f32 v80, v80, v81
	v_cvt_pk_bf16_f32 v81, v82, v83
	v_cvt_pk_bf16_f32 v82, v84, v85
	v_cvt_pk_bf16_f32 v83, v86, v87
	global_store_dwordx4 v78, v[80:83], s[38:39]
	s_sub_u32 s51, 0x4100, s51
	s_add_u32 s49, s49, s16
	s_add_u32 s50, s50, 1
	s_cmp_lt_u32 s49, s41
	s_cbranch_scc0 .LtcA_done

; template <bool FOLD>
; __device__ __forceinline__ void tconv_mat(const float* W, int K, int N, bf16_t* WT, const float* gam, const float* bet, float* cs, float* bw, LAS float* scr) {
;     ...
;         if (nx < nt) { const int tk2 = nx / tnn, tn2 = nx % tnn; const float* p = W + (size_t)(tk2 * 64 + kk) * N + tn2 * 64 + n4; v0 = __builtin_nontemporal_load((const f32x4*)p); v1 = __builtin_nontemporal_load((const f32x4*)(p + (size_t)32 * N)); }
;         scr[(n4 + 0) * 65 + kk] = w0[0]; scr[(n4 + 1) * 65 + kk] = w0[1]; scr[(n4 + 2) * 65 + kk] = w0[2]; scr[(n4 + 3) * 65 + kk] = w0[3];
;         scr[(n4 + 0) * 65 + kk + 32] = w1[0]; scr[(n4 + 1) * 65 + kk + 32] = w1[1]; scr[(n4 + 2) * 65 + kk + 32] = w1[2]; scr[(n4 + 3) * 65 + kk + 32] = w1[3];
;         __syncthreads();
.LtcA_wd_1:
	s_mul_hi_u32 s54, s49, s44
	s_mul_i32 s55, s54, s40
	s_sub_u32 s55, s49, s55
	v_add_u32_e32 v76, s51, v93
	ds_write2_b32 v76, v58, v62 offset1:32
	ds_write2_b32 v76, v59, v63 offset0:65 offset1:97
	ds_write2_b32 v76, v60, v64 offset0:130 offset1:162
	ds_write2_b32 v76, v61, v65 offset0:195 offset1:227
	s_waitcnt lgkmcnt(0)
	s_barrier
	s_mul_i32 s56, s55, s48
	s_lshl_b32 s57, s54, 7
	s_add_u32 s56, s56, s57
	v_add_u32_e32 v78, s56, v95
	s_add_u32 s52, s49, s34
	s_cmp_lt_u32 s52, s41
	s_cbranch_scc0 .LtcA_nl_1
	s_mul_hi_u32 s54, s52, s44
	s_mul_i32 s55, s54, s40
	s_sub_u32 s55, s52, s55
	s_mul_i32 s56, s54, s47
	s_lshl_b32 s57, s55, 8
	s_add_u32 s56, s56, s57
	v_add_u32_e32 v74, s56, v92
	v_add_u32_e32 v75, s46, v74
	global_load_dwordx4 v[58:61], v74, s[36:37] nt
	global_load_dwordx4 v[62:65], v75, s[36:37] nt

; __device__ __forceinline__ unsigned pk2(float lo, float hi) { return pg8::cvt_pk_bf16(lo, hi); }
; template <bool FOLD>
; __device__ __forceinline__ void tconv_mat(const float* W, int K, int N, bf16_t* WT, const float* gam, const float* bet, float* cs, float* bw, LAS float* scr) {
;     ...
;         scr[(n4 + 0) * 65 + kk] = w0[0]; scr[(n4 + 1) * 65 + kk] = w0[1]; scr[(n4 + 2) * 65 + kk] = w0[2]; scr[(n4 + 3) * 65 + kk] = w0[3];
;         scr[(n4 + 0) * 65 + kk + 32] = w1[0]; scr[(n4 + 1) * 65 + kk + 32] = w1[1]; scr[(n4 + 2) * 65 + kk + 32] = w1[2]; scr[(n4 + 3) * 65 + kk + 32] = w1[3];
;         __syncthreads();
;         { float x[8]; float bsum = 0.f, csum = 0.f;
;           if (FOLD) { const f32x4 g0 = *(const f32x4*)(gam + tk * 64 + k8), g1 = *(const f32x4*)(gam + tk * 64 + k8 + 4), b0 = *(const f32x4*)(bet + tk * 64 + k8), b1 = *(const f32x4*)(bet + tk * 64 + k8 + 4);
; #pragma unroll
;               for (int j = 0; j < 8; ++j) { const float xv = scr[n * 65 + k8 + j]; bsum += xv * (j < 4 ? b0[j & 3] : b1[j & 3]); x[j] = xv * (j < 4 ? g0[j & 3] : g1[j & 3]); }
;           } else {
; #pragma unroll
;               for (int j = 0; j < 8; ++j) x[j] = scr[n * 65 + k8 + j]; }
;           u32x4 w; w.x = pk2(x[0], x[1]); w.y = pk2(x[2], x[3]); w.z = pk2(x[4], x[5]); w.w = pk2(x[6], x[7]);
;           *(u32x4*)(WT + (size_t)(tn * 64 + n) * K + tk * 64 + k8) = w;
;           if (FOLD) {
; #pragma unroll
;               for (int c = 0; c < 4; ++c) csum += __uint_as_float(w[c] << 16) + __uint_as_float(w[c] & 0xffff0000u);
;               csum += __shfl_xor(csum, 1); bsum += __shfl_xor(bsum, 1); csum += __shfl_xor(csum, 2); bsum += __shfl_xor(bsum, 2); csum += __shfl_xor(csum, 4); bsum += __shfl_xor(bsum, 4);
;               if ((tid & 7) == 0) { __hip_atomic_fetch_add(cs + tn * 64 + n, csum, __ATOMIC_RELAXED, __HIP_MEMORY_SCOPE_AGENT); __hip_atomic_fetch_add(bw + tn * 64 + n, bsum, __ATOMIC_RELAXED, __HIP_MEMORY_SCOPE_AGENT); } } }
;         __syncthreads();
;         if (nx >= nt) break;
;         it = nx;
.LtcA_wd_2:
	s_mul_hi_u32 s54, s49, s44
	s_mul_i32 s55, s54, s40
	s_sub_u32 s55, s49, s55
	v_add_u32_e32 v76, s51, v93
	ds_write2_b32 v76, v66, v70 offset1:32
	ds_write2_b32 v76, v67, v71 offset0:65 offset1:97
	ds_write2_b32 v76, v68, v72 offset0:130 offset1:162
	ds_write2_b32 v76, v69, v73 offset0:195 offset1:227
	s_waitcnt lgkmcnt(0)
	s_barrier
	s_mul_i32 s56, s55, s48
	s_lshl_b32 s57, s54, 7
	s_add_u32 s56, s56, s57
	v_add_u32_e32 v78, s56, v95
	s_add_u32 s52, s49, s34
	s_cmp_lt_u32 s52, s41
	s_cbranch_scc0 .LtcA_nl_2
	s_mul_hi_u32 s54, s52, s44
	s_mul_i32 s55, s54, s40
	s_sub_u32 s55, s52, s55
	s_mul_i32 s56, s54, s47
	s_lshl_b32 s57, s55, 8
	s_add_u32 s56, s56, s57
	v_add_u32_e32 v74, s56, v92
	v_add_u32_e32 v75, s46, v74
	global_load_dwordx4 v[66:69], v74, s[36:37] nt
	global_load_dwordx4 v[70:73], v75, s[36:37] nt
.LtcA_nl_2:
	v_add_u32_e32 v77, s51, v94
	ds_read2_b32 v[80:81], v77 offset1:1
	ds_read2_b32 v[82:83], v77 offset0:2 offset1:3
	ds_read2_b32 v[84:85], v77 offset0:4 offset1:5
	ds_read2_b32 v[86:87], v77 offset0:6 offset1:7
	s_waitcnt lgkmcnt(0)
	v_cvt_pk_bf16_f32 v80, v80, v81
	v_cvt_pk_bf16_f32 v81, v82, v83
	v_cvt_pk_bf16_f32 v82, v84, v85
	v_cvt_pk_bf16_f32 v83, v86, v87
	global_store_dwordx4 v78, v[80:83], s[38:39]
	s_sub_u32 s51, 0x4100, s51
	s_add_u32 s49, s49, s16
	s_add_u32 s50, s50, 1
	s_cmp_lt_u32 s49, s41
	s_cbranch_scc0 .LtcA_done
	s_branch .LtcA_body0

; #define LAS __attribute__((address_space(3)))
; __device__ __forceinline__ void tconv_matrix_fold(const float* W, int K, int N, bf16_t* WT, const float* gam, const float* bet, float* cs, float* bw, LAS float* scr) { tconv_mat<true>(W, K, N, WT, gam, bet, cs, bw, scr); }
; #define AIN(i) (kargs()->in[i])
; #define CSUP(l) FOLDV(l, 0)
; #define BWUP(l) FOLDV(l, 8192)
; template <bool FOLD>
; __device__ __forceinline__ void tconv_mat(const float* W, int K, int N, bf16_t* WT, const float* gam, const float* bet, float* cs, float* bw, LAS float* scr) {
;     const int tkn = K / 64, tnn = N / 64, nt = tkn * tnn, tid = threadIdx.x;
;     const int kk = tid >> 4, n4 = (tid & 15) * 4, n = tid >> 3, k8 = (tid & 7) * 8;
;     int it = blockIdx.x; if (it >= nt) return;
;     f32x4 v0, v1;
;     { const int tk = it / tnn, tn = it % tnn; const float* p = W + (size_t)(tk * 64 + kk) * N + tn * 64 + n4; v0 = __builtin_nontemporal_load((const f32x4*)p); v1 = __builtin_nontemporal_load((const f32x4*)(p + (size_t)32 * N)); }
;     for (;;) {
;         const int tk = it / tnn, tn = it % tnn, nx = it + (int)gridDim.x;
;         const f32x4 w0 = v0, w1 = v1;
;         if (nx < nt) { const int tk2 = nx / tnn, tn2 = nx % tnn; const float* p = W + (size_t)(tk2 * 64 + kk) * N + tn2 * 64 + n4; v0 = __builtin_nontemporal_load((const f32x4*)p); v1 = __builtin_nontemporal_load((const f32x4*)(p + (size_t)32 * N)); }
;         scr[(n4 + 0) * 65 + kk] = w0[0]; scr[(n4 + 1) * 65 + kk] = w0[1]; scr[(n4 + 2) * 65 + kk] = w0[2]; scr[(n4 + 3) * 65 + kk] = w0[3];
;         scr[(n4 + 0) * 65 + kk + 32] = w1[0]; scr[(n4 + 1) * 65 + kk + 32] = w1[1]; scr[(n4 + 2) * 65 + kk + 32] = w1[2]; scr[(n4 + 3) * 65 + kk + 32] = w1[3];
;         __syncthreads();
;         { float x[8]; float bsum = 0.f, csum = 0.f;
;           if (FOLD) { const f32x4 g0 = *(const f32x4*)(gam + tk * 64 + k8), g1 = *(const f32x4*)(gam + tk * 64 + k8 + 4), b0 = *(const f32x4*)(bet + tk * 64 + k8), b1 = *(const f32x4*)(bet + tk * 64 + k8 + 4);
; #pragma unroll
;               for (int j = 0; j < 8; ++j) { const float xv = scr[n * 65 + k8 + j]; bsum += xv * (j < 4 ? b0[j & 3] : b1[j & 3]); x[j] = xv * (j < 4 ? g0[j & 3] : g1[j & 3]); }
; __global__ void __launch_bounds__(512, 2) fwd_mega(Args a) {
;     ...
;             tconv_matrix_fold(AIN(14), DM, DFF, (bf16_t*)(ws + WS_WUP), AIN(12), AIN(13), CSUP(0), BWUP(0), (LAS float*)lds);
.LBB0_73:
	s_load_dwordx2 s[36:37], s[0:1], 0x70
	s_load_dwordx2 s[10:11], s[0:1], 0x60
	s_load_dwordx2 s[12:13], s[0:1], 0x68
	s_add_u32 s28, s14, 0x180000
	s_addc_u32 s29, s15, 0
	s_add_u32 s68, s14, 0x188000
	s_addc_u32 s69, s15, 0
	s_add_u32 s38, s14, 0x2200000
	s_addc_u32 s39, s15, 0
	s_movk_i32 s40, 128
	s_movk_i32 s41, 4096
	s_mov_b32 s42, 0x8000
	s_mov_b32 s43, 0x1000
	s_mov_b32 s44, 0x2000000
	s_mov_b32 s45, 0
	s_waitcnt lgkmcnt(0)
	s_branch .LtcD_entry
.LtcD_entry:
	v_lshrrev_b32_e32 v88, 4, v241
	v_and_b32_e32 v89, 15, v241
	v_lshlrev_b32_e32 v89, 2, v89
	v_lshrrev_b32_e32 v90, 3, v241
	v_and_b32_e32 v91, 7, v241
	v_lshlrev_b32_e32 v91, 3, v91
	v_mul_lo_u32 v92, v88, s42
	v_lshl_add_u32 v92, v89, 2, v92
	v_mul_u32_u24_e32 v93, 0x104, v89
	v_lshl_add_u32 v93, v88, 2, v93
	v_mul_u32_u24_e32 v94, 0x104, v90
	v_lshl_add_u32 v94, v91, 2, v94
	v_mul_lo_u32 v95, v90, s43
	v_lshl_add_u32 v95, v91, 1, v95
	v_lshlrev_b32_e32 v96, 2, v91
	v_lshlrev_b32_e32 v97, 2, v90
	v_cmp_eq_u32_e32 vcc, 0, v91
	s_mov_b64 s[30:31], vcc
	s_lshl_b32 s46, s42, 5
	s_lshl_b32 s47, s42, 6
	s_lshl_b32 s48, s43, 6
	s_mov_b32 s49, s2
	s_mov_b32 s50, 0
	s_mov_b32 s51, 0
	s_lshl_b32 s58, s16, 1
	s_mul_i32 s34, s16, 3
	s_cmp_lt_u32 s49, s41
	s_cbranch_scc0 .LtcD_done
	s_mov_b32 s52, s49
	s_mul_hi_u32 s54, s52, s44
	s_mul_i32 s55, s54, s40
	s_sub_u32 s55, s52, s55
	s_mul_i32 s56, s54, s47
	s_lshl_b32 s57, s55, 8
	s_add_u32 s56, s56, s57
	v_add_u32_e32 v74, s56, v92
	v_add_u32_e32 v75, s46, v74
	global_load_dwordx4 v[50:53], v74, s[36:37] nt
	global_load_dwordx4 v[54:57], v75, s[36:37] nt
	s_add_u32 s52, s52, s16
	s_cmp_lt_u32 s52, s41
	s_cbranch_scc0 .LtcD_body0
	s_mul_hi_u32 s54, s52, s44
	s_mul_i32 s55, s54, s40
	s_sub_u32 s55, s52, s55
	s_mul_i32 s56, s54, s47
	s_lshl_b32 s57, s55, 8
	s_add_u32 s56, s56, s57
	v_add_u32_e32 v74, s56, v92
	v_add_u32_e32 v75, s46, v74
	global_load_dwordx4 v[58:61], v74, s[36:37] nt
	global_load_dwordx4 v[62:65], v75, s[36:37] nt
	s_add_u32 s52, s52, s16
	s_cmp_lt_u32 s52, s41
	s_cbranch_scc0 .LtcD_body0
	s_mul_hi_u32 s54, s52, s44
	s_mul_i32 s55, s54, s40
	s_sub_u32 s55, s52, s55
	s_mul_i32 s56, s54, s47
	s_lshl_b32 s57, s55, 8
	s_add_u32 s56, s56, s57
	v_add_u32_e32 v74, s56, v92
	v_add_u32_e32 v75, s46, v74
	global_load_dwordx4 v[66:69], v74, s[36:37] nt
	global_load_dwordx4 v[70:73], v75, s[36:37] nt
.LtcD_body0:
	s_add_u32 s59, s49, s58
	s_cmp_lt_u32 s59, s41
	s_cbranch_scc0 .LtcD_w0_0
	s_cmp_eq_u32 s50, 0
	s_cbranch_scc1 .LtcD_wi0_0
	s_cmp_eq_u32 s50, 1
	s_cbranch_scc1 .LtcD_wi1_0
	s_cmp_eq_u32 s50, 2
	s_cbranch_scc1 .LtcD_wi2_0
	s_waitcnt vmcnt(21)
	s_branch .LtcD_wd_0
.LtcD_wi2_0:
	s_waitcnt vmcnt(18)
	s_branch .LtcD_wd_0
.LtcD_wi1_0:
	s_waitcnt vmcnt(11)
	s_branch .LtcD_wd_0

; __device__ __forceinline__ unsigned pk2(float lo, float hi) { return pg8::cvt_pk_bf16(lo, hi); }
; template <bool FOLD>
; __device__ __forceinline__ void tconv_mat(const float* W, int K, int N, bf16_t* WT, const float* gam, const float* bet, float* cs, float* bw, LAS float* scr) {
;     ...
;         if (nx < nt) { const int tk2 = nx / tnn, tn2 = nx % tnn; const float* p = W + (size_t)(tk2 * 64 + kk) * N + tn2 * 64 + n4; v0 = __builtin_nontemporal_load((const f32x4*)p); v1 = __builtin_nontemporal_load((const f32x4*)(p + (size_t)32 * N)); }
;         scr[(n4 + 0) * 65 + kk] = w0[0]; scr[(n4 + 1) * 65 + kk] = w0[1]; scr[(n4 + 2) * 65 + kk] = w0[2]; scr[(n4 + 3) * 65 + kk] = w0[3];
;         scr[(n4 + 0) * 65 + kk + 32] = w1[0]; scr[(n4 + 1) * 65 + kk + 32] = w1[1]; scr[(n4 + 2) * 65 + kk + 32] = w1[2]; scr[(n4 + 3) * 65 + kk + 32] = w1[3];
;         __syncthreads();
;         { float x[8]; float bsum = 0.f, csum = 0.f;
;           if (FOLD) { const f32x4 g0 = *(const f32x4*)(gam + tk * 64 + k8), g1 = *(const f32x4*)(gam + tk * 64 + k8 + 4), b0 = *(const f32x4*)(bet + tk * 64 + k8), b1 = *(const f32x4*)(bet + tk * 64 + k8 + 4);
; #pragma unroll
;               for (int j = 0; j < 8; ++j) { const float xv = scr[n * 65 + k8 + j]; bsum += xv * (j < 4 ? b0[j & 3] : b1[j & 3]); x[j] = xv * (j < 4 ? g0[j & 3] : g1[j & 3]); }
;           } else {
; #pragma unroll
;               for (int j = 0; j < 8; ++j) x[j] = scr[n * 65 + k8 + j]; }
;           u32x4 w; w.x = pk2(x[0], x[1]); w.y = pk2(x[2], x[3]); w.z = pk2(x[4], x[5]); w.w = pk2(x[6], x[7]);
;           *(u32x4*)(WT + (size_t)(tn * 64 + n) * K + tk * 64 + k8) = w;
.LtcD_wd_0:
	s_mul_hi_u32 s54, s49, s44
	s_mul_i32 s55, s54, s40
	s_sub_u32 s55, s49, s55
	s_lshl_b32 s53, s54, 8
	v_add_u32_e32 v79, s53, v96
	global_load_dwordx4 v[100:103], v79, s[10:11]
	global_load_dwordx4 v[104:107], v79, s[10:11] offset:16
	global_load_dwordx4 v[108:111], v79, s[12:13]
	global_load_dwordx4 v[112:115], v79, s[12:13] offset:16
	v_add_u32_e32 v76, s51, v93
	ds_write2_b32 v76, v50, v54 offset1:32
	ds_write2_b32 v76, v51, v55 offset0:65 offset1:97
	ds_write2_b32 v76, v52, v56 offset0:130 offset1:162
	ds_write2_b32 v76, v53, v57 offset0:195 offset1:227
	s_waitcnt lgkmcnt(0)
	s_barrier
	s_mul_i32 s56, s55, s48
	s_lshl_b32 s57, s54, 7
	s_add_u32 s56, s56, s57
	v_add_u32_e32 v78, s56, v95
	s_lshl_b32 s53, s55, 8
	v_add_u32_e32 v98, s53, v97
	s_add_u32 s52, s49, s34
	s_cmp_lt_u32 s52, s41
	s_cselect_b32 s53, 1, 0
	s_cbranch_scc0 .LtcD_nl_0
	s_mul_hi_u32 s54, s52, s44
	s_mul_i32 s55, s54, s40
	s_sub_u32 s55, s52, s55
	s_mul_i32 s56, s54, s47
	s_lshl_b32 s57, s55, 8
	s_add_u32 s56, s56, s57
	v_add_u32_e32 v74, s56, v92
	v_add_u32_e32 v75, s46, v74
	global_load_dwordx4 v[50:53], v74, s[36:37] nt
	global_load_dwordx4 v[54:57], v75, s[36:37] nt
.LtcD_nl_0:
	v_add_u32_e32 v77, s51, v94
	ds_read2_b32 v[80:81], v77 offset1:1
	ds_read2_b32 v[82:83], v77 offset0:2 offset1:3
	ds_read2_b32 v[84:85], v77 offset0:4 offset1:5
	ds_read2_b32 v[86:87], v77 offset0:6 offset1:7
	s_cmp_eq_u32 s53, 1
	s_cbranch_scc0 .LtcD_g0_0
	s_waitcnt vmcnt(2)
	s_branch .LtcD_gd_0

; __device__ __forceinline__ unsigned pk2(float lo, float hi) { return pg8::cvt_pk_bf16(lo, hi); }
; template <bool FOLD>
; __device__ __forceinline__ void tconv_mat(const float* W, int K, int N, bf16_t* WT, const float* gam, const float* bet, float* cs, float* bw, LAS float* scr) {
;     ...
;           if (FOLD) { const f32x4 g0 = *(const f32x4*)(gam + tk * 64 + k8), g1 = *(const f32x4*)(gam + tk * 64 + k8 + 4), b0 = *(const f32x4*)(bet + tk * 64 + k8), b1 = *(const f32x4*)(bet + tk * 64 + k8 + 4);
; #pragma unroll
;               for (int j = 0; j < 8; ++j) { const float xv = scr[n * 65 + k8 + j]; bsum += xv * (j < 4 ? b0[j & 3] : b1[j & 3]); x[j] = xv * (j < 4 ? g0[j & 3] : g1[j & 3]); }
;           } else {
; #pragma unroll
;               for (int j = 0; j < 8; ++j) x[j] = scr[n * 65 + k8 + j]; }
;           u32x4 w; w.x = pk2(x[0], x[1]); w.y = pk2(x[2], x[3]); w.z = pk2(x[4], x[5]); w.w = pk2(x[6], x[7]);
;           *(u32x4*)(WT + (size_t)(tn * 64 + n) * K + tk * 64 + k8) = w;
;           if (FOLD) {
; #pragma unroll
;               for (int c = 0; c < 4; ++c) csum += __uint_as_float(w[c] << 16) + __uint_as_float(w[c] & 0xffff0000u);
;               csum += __shfl_xor(csum, 1); bsum += __shfl_xor(bsum, 1); csum += __shfl_xor(csum, 2); bsum += __shfl_xor(bsum, 2); csum += __shfl_xor(csum, 4); bsum += __shfl_xor(bsum, 4);
;               if ((tid & 7) == 0) { __hip_atomic_fetch_add(cs + tn * 64 + n, csum, __ATOMIC_RELAXED, __HIP_MEMORY_SCOPE_AGENT); __hip_atomic_fetch_add(bw + tn * 64 + n, bsum, __ATOMIC_RELAXED, __HIP_MEMORY_SCOPE_AGENT); } } }
.LtcD_gd_0:
	s_waitcnt lgkmcnt(0)
	v_mul_f32_e32 v116, v80, v108
	v_fmac_f32_e32 v116, v81, v109
	v_fmac_f32_e32 v116, v82, v110
	v_fmac_f32_e32 v116, v83, v111
	v_fmac_f32_e32 v116, v84, v112
	v_fmac_f32_e32 v116, v85, v113
	v_fmac_f32_e32 v116, v86, v114
	v_fmac_f32_e32 v116, v87, v115
	v_mul_f32_e32 v80, v80, v100
	v_mul_f32_e32 v81, v81, v101
	v_mul_f32_e32 v82, v82, v102
	v_mul_f32_e32 v83, v83, v103
	v_mul_f32_e32 v84, v84, v104
	v_mul_f32_e32 v85, v85, v105
	v_mul_f32_e32 v86, v86, v106
	v_mul_f32_e32 v87, v87, v107
	v_cvt_pk_bf16_f32 v80, v80, v81
	v_cvt_pk_bf16_f32 v81, v82, v83
	v_cvt_pk_bf16_f32 v82, v84, v85
	v_cvt_pk_bf16_f32 v83, v86, v87
	global_store_dwordx4 v78, v[80:83], s[38:39]
	v_lshlrev_b32_e32 v117, 16, v80
	v_and_b32_e32 v118, 0xffff0000, v80
	v_add_f32_e32 v119, v117, v118
	v_lshlrev_b32_e32 v117, 16, v81
	v_and_b32_e32 v118, 0xffff0000, v81
	v_add_f32_e32 v117, v117, v118
	v_add_f32_e32 v119, v119, v117
	v_lshlrev_b32_e32 v117, 16, v82
	v_and_b32_e32 v118, 0xffff0000, v82
	v_add_f32_e32 v117, v117, v118
	v_add_f32_e32 v119, v119, v117
	v_lshlrev_b32_e32 v117, 16, v83
	v_and_b32_e32 v118, 0xffff0000, v83
	v_add_f32_e32 v117, v117, v118
	v_add_f32_e32 v119, v119, v117
	s_nop 1
	v_add_f32_dpp v119, v119, v119 quad_perm:[1,0,3,2] row_mask:0xf bank_mask:0xf
	v_add_f32_dpp v116, v116, v116 quad_perm:[1,0,3,2] row_mask:0xf bank_mask:0xf
	s_nop 1
	v_add_f32_dpp v119, v119, v119 quad_perm:[2,3,0,1] row_mask:0xf bank_mask:0xf
	v_add_f32_dpp v116, v116, v116 quad_perm:[2,3,0,1] row_mask:0xf bank_mask:0xf
	s_nop 1
	v_add_f32_dpp v119, v119, v119 row_half_mirror row_mask:0xf bank_mask:0xf
	v_add_f32_dpp v116, v116, v116 row_half_mirror row_mask:0xf bank_mask:0xf
	s_mov_b64 exec, s[30:31]
	global_atomic_add_f32 v98, v119, s[28:29]
	global_atomic_add_f32 v98, v116, s[68:69]
	s_mov_b64 exec, -1
	s_sub_u32 s51, 0x4100, s51
	s_add_u32 s49, s49, s16
	s_add_u32 s50, s50, 1
	s_cmp_lt_u32 s49, s41
	s_cbranch_scc0 .LtcD_done

; template <bool FOLD>
; __device__ __forceinline__ void tconv_mat(const float* W, int K, int N, bf16_t* WT, const float* gam, const float* bet, float* cs, float* bw, LAS float* scr) {
;     ...
;         if (nx < nt) { const int tk2 = nx / tnn, tn2 = nx % tnn; const float* p = W + (size_t)(tk2 * 64 + kk) * N + tn2 * 64 + n4; v0 = __builtin_nontemporal_load((const f32x4*)p); v1 = __builtin_nontemporal_load((const f32x4*)(p + (size_t)32 * N)); }
;         scr[(n4 + 0) * 65 + kk] = w0[0]; scr[(n4 + 1) * 65 + kk] = w0[1]; scr[(n4 + 2) * 65 + kk] = w0[2]; scr[(n4 + 3) * 65 + kk] = w0[3];
;         scr[(n4 + 0) * 65 + kk + 32] = w1[0]; scr[(n4 + 1) * 65 + kk + 32] = w1[1]; scr[(n4 + 2) * 65 + kk + 32] = w1[2]; scr[(n4 + 3) * 65 + kk + 32] = w1[3];
;         __syncthreads();
;         { float x[8]; float bsum = 0.f, csum = 0.f;
;           if (FOLD) { const f32x4 g0 = *(const f32x4*)(gam + tk * 64 + k8), g1 = *(const f32x4*)(gam + tk * 64 + k8 + 4), b0 = *(const f32x4*)(bet + tk * 64 + k8), b1 = *(const f32x4*)(bet + tk * 64 + k8 + 4);
.LtcD_wd_1:
	s_mul_hi_u32 s54, s49, s44
	s_mul_i32 s55, s54, s40
	s_sub_u32 s55, s49, s55
	s_lshl_b32 s53, s54, 8
	v_add_u32_e32 v79, s53, v96
	global_load_dwordx4 v[100:103], v79, s[10:11]
	global_load_dwordx4 v[104:107], v79, s[10:11] offset:16
	global_load_dwordx4 v[108:111], v79, s[12:13]
	global_load_dwordx4 v[112:115], v79, s[12:13] offset:16
	v_add_u32_e32 v76, s51, v93
	ds_write2_b32 v76, v58, v62 offset1:32
	ds_write2_b32 v76, v59, v63 offset0:65 offset1:97
	ds_write2_b32 v76, v60, v64 offset0:130 offset1:162
	ds_write2_b32 v76, v61, v65 offset0:195 offset1:227
	s_waitcnt lgkmcnt(0)
	s_barrier
	s_mul_i32 s56, s55, s48
	s_lshl_b32 s57, s54, 7
	s_add_u32 s56, s56, s57
	v_add_u32_e32 v78, s56, v95
	s_lshl_b32 s53, s55, 8
	v_add_u32_e32 v98, s53, v97
	s_add_u32 s52, s49, s34
	s_cmp_lt_u32 s52, s41
	s_cselect_b32 s53, 1, 0
	s_cbranch_scc0 .LtcD_nl_1
	s_mul_hi_u32 s54, s52, s44
	s_mul_i32 s55, s54, s40
	s_sub_u32 s55, s52, s55
	s_mul_i32 s56, s54, s47
	s_lshl_b32 s57, s55, 8
	s_add_u32 s56, s56, s57
	v_add_u32_e32 v74, s56, v92
	v_add_u32_e32 v75, s46, v74
	global_load_dwordx4 v[58:61], v74, s[36:37] nt
	global_load_dwordx4 v[62:65], v75, s[36:37] nt

; template <bool FOLD>
; __device__ __forceinline__ void tconv_mat(const float* W, int K, int N, bf16_t* WT, const float* gam, const float* bet, float* cs, float* bw, LAS float* scr) {
;     ...
;         if (nx < nt) { const int tk2 = nx / tnn, tn2 = nx % tnn; const float* p = W + (size_t)(tk2 * 64 + kk) * N + tn2 * 64 + n4; v0 = __builtin_nontemporal_load((const f32x4*)p); v1 = __builtin_nontemporal_load((const f32x4*)(p + (size_t)32 * N)); }
;         scr[(n4 + 0) * 65 + kk] = w0[0]; scr[(n4 + 1) * 65 + kk] = w0[1]; scr[(n4 + 2) * 65 + kk] = w0[2]; scr[(n4 + 3) * 65 + kk] = w0[3];
;         scr[(n4 + 0) * 65 + kk + 32] = w1[0]; scr[(n4 + 1) * 65 + kk + 32] = w1[1]; scr[(n4 + 2) * 65 + kk + 32] = w1[2]; scr[(n4 + 3) * 65 + kk + 32] = w1[3];
;         __syncthreads();
;         { float x[8]; float bsum = 0.f, csum = 0.f;
;           if (FOLD) { const f32x4 g0 = *(const f32x4*)(gam + tk * 64 + k8), g1 = *(const f32x4*)(gam + tk * 64 + k8 + 4), b0 = *(const f32x4*)(bet + tk * 64 + k8), b1 = *(const f32x4*)(bet + tk * 64 + k8 + 4);
.LtcD_wd_2:
	s_mul_hi_u32 s54, s49, s44
	s_mul_i32 s55, s54, s40
	s_sub_u32 s55, s49, s55
	s_lshl_b32 s53, s54, 8
	v_add_u32_e32 v79, s53, v96
	global_load_dwordx4 v[100:103], v79, s[10:11]
	global_load_dwordx4 v[104:107], v79, s[10:11] offset:16
	global_load_dwordx4 v[108:111], v79, s[12:13]
	global_load_dwordx4 v[112:115], v79, s[12:13] offset:16
	v_add_u32_e32 v76, s51, v93
	ds_write2_b32 v76, v66, v70 offset1:32
	ds_write2_b32 v76, v67, v71 offset0:65 offset1:97
	ds_write2_b32 v76, v68, v72 offset0:130 offset1:162
	ds_write2_b32 v76, v69, v73 offset0:195 offset1:227
	s_waitcnt lgkmcnt(0)
	s_barrier
	s_mul_i32 s56, s55, s48
	s_lshl_b32 s57, s54, 7
	s_add_u32 s56, s56, s57
	v_add_u32_e32 v78, s56, v95
	s_lshl_b32 s53, s55, 8
	v_add_u32_e32 v98, s53, v97
	s_add_u32 s52, s49, s34
	s_cmp_lt_u32 s52, s41
	s_cselect_b32 s53, 1, 0
	s_cbranch_scc0 .LtcD_nl_2
	s_mul_hi_u32 s54, s52, s44
	s_mul_i32 s55, s54, s40
	s_sub_u32 s55, s52, s55
	s_mul_i32 s56, s54, s47
	s_lshl_b32 s57, s55, 8
	s_add_u32 s56, s56, s57
	v_add_u32_e32 v74, s56, v92
	v_add_u32_e32 v75, s46, v74
	global_load_dwordx4 v[66:69], v74, s[36:37] nt
	global_load_dwordx4 v[70:73], v75, s[36:37] nt

; #define LAS __attribute__((address_space(3)))
; __device__ __forceinline__ unsigned pk2(float lo, float hi) { return pg8::cvt_pk_bf16(lo, hi); }
; __device__ __forceinline__ unsigned xb_xcc_id() { return (unsigned)__builtin_amdgcn_s_getreg((3 << 11) | 20) & 0xFu; }
; template <bool FOLD>
; __device__ __forceinline__ void tconv_mat(const float* W, int K, int N, bf16_t* WT, const float* gam, const float* bet, float* cs, float* bw, LAS float* scr) {
;     ...
;           if (FOLD) { const f32x4 g0 = *(const f32x4*)(gam + tk * 64 + k8), g1 = *(const f32x4*)(gam + tk * 64 + k8 + 4), b0 = *(const f32x4*)(bet + tk * 64 + k8), b1 = *(const f32x4*)(bet + tk * 64 + k8 + 4);
; #pragma unroll
;               for (int j = 0; j < 8; ++j) { const float xv = scr[n * 65 + k8 + j]; bsum += xv * (j < 4 ? b0[j & 3] : b1[j & 3]); x[j] = xv * (j < 4 ? g0[j & 3] : g1[j & 3]); }
;           } else {
; #pragma unroll
;               for (int j = 0; j < 8; ++j) x[j] = scr[n * 65 + k8 + j]; }
;           u32x4 w; w.x = pk2(x[0], x[1]); w.y = pk2(x[2], x[3]); w.z = pk2(x[4], x[5]); w.w = pk2(x[6], x[7]);
;           *(u32x4*)(WT + (size_t)(tn * 64 + n) * K + tk * 64 + k8) = w;
;           if (FOLD) {
; #pragma unroll
;               for (int c = 0; c < 4; ++c) csum += __uint_as_float(w[c] << 16) + __uint_as_float(w[c] & 0xffff0000u);
;               csum += __shfl_xor(csum, 1); bsum += __shfl_xor(bsum, 1); csum += __shfl_xor(csum, 2); bsum += __shfl_xor(bsum, 2); csum += __shfl_xor(csum, 4); bsum += __shfl_xor(bsum, 4);
;               if ((tid & 7) == 0) { __hip_atomic_fetch_add(cs + tn * 64 + n, csum, __ATOMIC_RELAXED, __HIP_MEMORY_SCOPE_AGENT); __hip_atomic_fetch_add(bw + tn * 64 + n, bsum, __ATOMIC_RELAXED, __HIP_MEMORY_SCOPE_AGENT); } } }
;         __syncthreads();
;         if (nx >= nt) break;
;         it = nx;
;     }
; }
; __device__ __forceinline__ void xcd_barrier(unsigned* bar, volatile LAS unsigned* st) {
;     asm volatile("s_waitcnt vmcnt(0)" ::: "memory");
;     __syncthreads();
;     if (threadIdx.x == 0) {
;         __builtin_amdgcn_s_waitcnt(0);
;         const unsigned x = xb_xcc_id();
;         unsigned nloc = st[0], nx = st[1];
;         if (nloc == 0u) { xcd_barrier_complete(bar, x, nloc, nx); st[0] = nloc; st[1] = nx; }
.LtcD_gd_2:
	s_waitcnt lgkmcnt(0)
	v_mul_f32_e32 v116, v80, v108
	v_fmac_f32_e32 v116, v81, v109
	v_fmac_f32_e32 v116, v82, v110
	v_fmac_f32_e32 v116, v83, v111
	v_fmac_f32_e32 v116, v84, v112
	v_fmac_f32_e32 v116, v85, v113
	v_fmac_f32_e32 v116, v86, v114
	v_fmac_f32_e32 v116, v87, v115
	v_mul_f32_e32 v80, v80, v100
	v_mul_f32_e32 v81, v81, v101
	v_mul_f32_e32 v82, v82, v102
	v_mul_f32_e32 v83, v83, v103
	v_mul_f32_e32 v84, v84, v104
	v_mul_f32_e32 v85, v85, v105
	v_mul_f32_e32 v86, v86, v106
	v_mul_f32_e32 v87, v87, v107
	v_cvt_pk_bf16_f32 v80, v80, v81
	v_cvt_pk_bf16_f32 v81, v82, v83
	v_cvt_pk_bf16_f32 v82, v84, v85
	v_cvt_pk_bf16_f32 v83, v86, v87
	global_store_dwordx4 v78, v[80:83], s[38:39]
	v_lshlrev_b32_e32 v117, 16, v80
	v_and_b32_e32 v118, 0xffff0000, v80
	v_add_f32_e32 v119, v117, v118
	v_lshlrev_b32_e32 v117, 16, v81
	v_and_b32_e32 v118, 0xffff0000, v81
	v_add_f32_e32 v117, v117, v118
	v_add_f32_e32 v119, v119, v117
	v_lshlrev_b32_e32 v117, 16, v82
	v_and_b32_e32 v118, 0xffff0000, v82
	v_add_f32_e32 v117, v117, v118
	v_add_f32_e32 v119, v119, v117
	v_lshlrev_b32_e32 v117, 16, v83
	v_and_b32_e32 v118, 0xffff0000, v83
	v_add_f32_e32 v117, v117, v118
	v_add_f32_e32 v119, v119, v117
	s_nop 1
	v_add_f32_dpp v119, v119, v119 quad_perm:[1,0,3,2] row_mask:0xf bank_mask:0xf
	v_add_f32_dpp v116, v116, v116 quad_perm:[1,0,3,2] row_mask:0xf bank_mask:0xf
	s_nop 1
	v_add_f32_dpp v119, v119, v119 quad_perm:[2,3,0,1] row_mask:0xf bank_mask:0xf
	v_add_f32_dpp v116, v116, v116 quad_perm:[2,3,0,1] row_mask:0xf bank_mask:0xf
	s_nop 1
	v_add_f32_dpp v119, v119, v119 row_half_mirror row_mask:0xf bank_mask:0xf
	v_add_f32_dpp v116, v116, v116 row_half_mirror row_mask:0xf bank_mask:0xf
	s_mov_b64 exec, s[30:31]
	global_atomic_add_f32 v98, v119, s[28:29]
	global_atomic_add_f32 v98, v116, s[68:69]
	s_mov_b64 exec, -1
	s_sub_u32 s51, 0x4100, s51
	s_add_u32 s49, s49, s16
	s_add_u32 s50, s50, 1
	s_cmp_lt_u32 s49, s41
	s_cbranch_scc0 .LtcD_done
	s_branch .LtcD_body0
.LtcD_done:
	s_barrier
	s_branch .LtcD_ret0
.LtcD_ret0:
.LBB0_80:
	s_cmp_gt_i32 s66, 2
	s_cselect_b64 s[4:5], -1, 0
	s_and_b64 s[6:7], s[6:7], s[4:5]
	s_andn2_b64 vcc, exec, s[6:7]
	s_cbranch_vccnz .LBB0_134
	s_waitcnt vmcnt(0)
	s_waitcnt vmcnt(0)
	s_barrier
	s_and_saveexec_b64 s[6:7], s[8:9]
	s_cbranch_execz .LBB0_133
	s_add_i32 s11, 0, 0x20600
	v_mov_b32_e32 v0, s11
	s_waitcnt vmcnt(0) expcnt(0) lgkmcnt(0)
	s_getreg_b32 s10, hwreg(HW_REG_XCC_ID, 0, 4)
	ds_read_b32 v2, v0
	s_add_i32 s11, 0, 0x20604
	v_mov_b32_e32 v0, s11
	ds_read_b32 v0, v0
	s_and_b32 s64, s10, 15
	s_waitcnt lgkmcnt(1)
	v_cmp_ne_u32_e32 vcc, 0, v2
	s_cbranch_vccnz .LBB0_97
	s_add_u32 s10, s14, 0x100200
	s_addc_u32 s11, s15, 0
	s_add_u32 s12, s14, 0x100400
	s_addc_u32 s13, s15, 0
	s_add_u32 s26, s14, 0x100500
	s_addc_u32 s27, s15, 0
	s_add_u32 s28, s14, 0x100600
	s_addc_u32 s29, s15, 0
	s_add_u32 s30, s14, 0x100700
	s_addc_u32 s31, s15, 0
	s_add_u32 s34, s14, 0x100800
	s_addc_u32 s35, s15, 0
	s_add_u32 s36, s14, 0x100900
	s_addc_u32 s37, s15, 0
	s_add_u32 s38, s14, 0x100a00
	s_addc_u32 s39, s15, 0
	s_add_u32 s40, s14, 0x100b00
	s_addc_u32 s41, s15, 0
	s_add_u32 s42, s14, 0x100c00
	s_addc_u32 s43, s15, 0
	s_add_u32 s44, s14, 0x100d00
	s_addc_u32 s45, s15, 0
	s_add_u32 s46, s14, 0x100e00
	s_addc_u32 s47, s15, 0
	s_add_u32 s48, s14, 0x100f00
	s_addc_u32 s49, s15, 0
	s_add_u32 s50, s14, 0x101000
	s_addc_u32 s51, s15, 0
	s_add_u32 s52, s14, 0x101100
	s_addc_u32 s53, s15, 0
	s_add_u32 s54, s14, 0x101200
	s_addc_u32 s55, s15, 0
	s_mul_i32 s65, s17, s33
	s_add_u32 s56, s14, 0x101300
	s_mul_i32 s65, s65, s16
	s_addc_u32 s57, s15, 0
	s_mov_b32 s67, 1
	v_mov_b32_e32 v16, 0
	s_branch .LBB0_85

; #define LAS __attribute__((address_space(3)))
; __device__ __forceinline__ void tconv_matrix_fold(const float* W, int K, int N, bf16_t* WT, const float* gam, const float* bet, float* cs, float* bw, LAS float* scr) { tconv_mat<true>(W, K, N, WT, gam, bet, cs, bw, scr); }
; #define AIN(i) (kargs()->in[i])
; #define CSIN(l) FOLDV(l, 16384)
; #define BWIN(l) FOLDV(l, 22528)
; __global__ void __launch_bounds__(512, 2) fwd_mega(Args a) {
;     ...
;         if (IN(pb + 5)) {
;             tconv_matrix_fold(AIN(3) + (size_t)DM * INW, DM, INW, (bf16_t*)(ws + WS_WIN), AIN(16), AIN(17), CSIN(1), BWIN(1), (LAS float*)lds);
.LBB0_586:
	s_cmp_lt_i32 s3, 7
	s_cselect_b64 s[6:7], -1, 0
	s_and_b64 s[6:7], s[6:7], s[4:5]
	s_andn2_b64 vcc, exec, s[6:7]
	s_cbranch_vccnz .LBB0_615
	s_load_dwordx2 s[36:37], s[0:1], 0x18
	s_load_dwordx2 s[10:11], s[0:1], 0x80
	s_load_dwordx2 s[12:13], s[0:1], 0x88
	s_add_u32 s28, s14, 0x1ac000
	s_addc_u32 s29, s15, 0
	s_add_u32 s68, s14, 0x1b2000
	s_addc_u32 s69, s15, 0
	s_add_u32 s38, s14, 0x200000
	s_addc_u32 s39, s15, 0
	s_movk_i32 s40, 96
	s_movk_i32 s41, 3072
	s_mov_b32 s42, 0x6000
	s_mov_b32 s43, 0x1000
	s_mov_b32 s44, 0x2aaaaab
	s_mov_b32 s45, 0
	s_waitcnt lgkmcnt(0)
	s_add_u32 s36, s36, 0x3000000
	s_addc_u32 s37, s37, 0
	s_branch .LtcC_entry

; #define LAS __attribute__((address_space(3)))
; __device__ __forceinline__ void tconv_matrix_fold(const float* W, int K, int N, bf16_t* WT, const float* gam, const float* bet, float* cs, float* bw, LAS float* scr) { tconv_mat<true>(W, K, N, WT, gam, bet, cs, bw, scr); }
; #define AIN(i) (kargs()->in[i])
; #define CSUP(l) FOLDV(l, 0)
; #define BWUP(l) FOLDV(l, 8192)
; __global__ void __launch_bounds__(512, 2) fwd_mega(Args a) {
;     ...
;             tconv_matrix_fold(AIN(14) + (size_t)DM * DFF, DM, DFF, (bf16_t*)(ws + WS_WUP), AIN(12) + DM, AIN(13) + DM, CSUP(1), BWUP(1), (LAS float*)lds);
.LtcB_ret0:
	s_load_dwordx2 s[36:37], s[0:1], 0x70
	s_load_dwordx2 s[10:11], s[0:1], 0x60
	s_load_dwordx2 s[12:13], s[0:1], 0x68
	s_add_u32 s28, s14, 0x19c000
	s_addc_u32 s29, s15, 0
	s_add_u32 s68, s14, 0x1a4000
	s_addc_u32 s69, s15, 0
	s_add_u32 s38, s14, 0x2200000
	s_addc_u32 s39, s15, 0
	s_movk_i32 s40, 128
	s_movk_i32 s41, 4096
	s_mov_b32 s42, 0x8000
	s_mov_b32 s43, 0x1000
	s_mov_b32 s44, 0x2000000
	s_mov_b32 s45, 1
	s_waitcnt lgkmcnt(0)
	s_add_u32 s36, s36, 0x4000000
	s_addc_u32 s37, s37, 0
	s_add_u32 s10, s10, 0x2000
	s_addc_u32 s11, s11, 0
	s_add_u32 s12, s12, 0x2000
	s_addc_u32 s13, s13, 0
	s_branch .LtcC_entry
